# phase 3: GLA main-item workgroups take 4 transpose iterations (tiles 832..1855) after their item; sample workgroups do the remaining 16
# baseline (speedup 1.0000x reference)
.LBB0_362:
	s_cmp_lt_u32 s2, 0
	s_cbranch_scc1 .Ltrm_skip
	s_cmp_ge_u32 s2, 128
	s_cbranch_scc1 .Ltrm_skip
	s_load_dword s4, s[0:1], 0x148
	s_waitcnt lgkmcnt(0)
	s_cmpk_lg_i32 s4, 0x100
	s_cbranch_scc1 .Ltrm_skip
	s_sub_u32 s3, s2, 0
	s_lshl_b32 s3, s3, 1
	s_addk_i32 s3, 0x340
	s_cmpk_gt_i32 s3, 0x73f
	s_cbranch_scc1 .Ltrm_done
	s_load_dwordx4 s[72:75], s[0:1], 0x48
	s_load_dwordx2 s[76:77], s[0:1], 0x78
	s_load_dwordx2 s[78:79], s[0:1], 0x80
	s_load_dwordx4 s[80:83], s[0:1], 0xc8
	s_load_dwordx4 s[84:87], s[0:1], 0x100
	v_and_b32_e32 v32, 63, v129
	v_lshlrev_b32_e32 v82, 2, v32
	v_mov_b32_e32 v83, 0
	v_lshrrev_b32_e32 v84, 5, v32
	v_lshlrev_b32_e32 v84, 4, v84
	v_and_b32_e32 v85, 15, v32
	v_add_u32_e32 v84, v84, v85
	v_lshlrev_b32_e32 v84, 2, v84
	v_mov_b32_e32 v85, 0
	v_and_b32_e32 v37, 16, v32
	v_cmp_ne_u32_e64 s[68:69], 0, v37
	v_readfirstlane_b32 s4, v129
	s_lshr_b32 s4, s4, 6
	s_lshr_b32 s5, s4, 2
	s_and_b32 s6, s4, 3
	s_lshl_b32 s7, s5, 15
	s_mul_i32 s8, s6, 0x104
	s_add_u32 s8, s7, s8
	v_add_u32_e32 v38, s8, v82
	v_and_b32_e32 v39, 7, v129
	v_lshlrev_b32_e32 v39, 3, v39
	v_mul_u32_u24_e32 v40, 0x104, v39
	v_bfe_u32 v41, v129, 3, 5
	v_lshl_add_u32 v40, v41, 2, v40
	v_add_u32_e32 v40, s7, v40
	v_add_u32_e32 v44, 0x400, v40
	v_lshlrev_b32_e32 v42, 1, v39
	v_mov_b32_e32 v47, 0
	s_add_u32 s9, s3, s5
	s_waitcnt lgkmcnt(0)
	s_cmpk_lt_u32 s9, 0x440
	s_cbranch_scc1 .Ltrm_p1_c0
	s_cmpk_lt_u32 s9, 0xc40
	s_cbranch_scc1 .Ltrm_p1_c1
	s_cmpk_lt_u32 s9, 0x1440
	s_cbranch_scc1 .Ltrm_p1_c2
	s_cmpk_lt_u32 s9, 0x1540
	s_cbranch_scc1 .Ltrm_p1_c3
	s_sub_u32 s7, s9, 0x1540
	s_mov_b64 s[70:71], s[80:81]
	s_mov_b64 s[12:13], s[82:83]
	s_mov_b64 s[16:17], s[86:87]
	s_mov_b32 s8, 10
	s_mov_b32 s22, 10
	s_mov_b32 s21, 1
	s_branch .Ltrm_p1_cm

.Ltrm_loop:
	s_addk_i32 s9, 0x100
	s_cmpk_lt_u32 s9, 0x740
	s_cbranch_scc0 .Ltrm_last1
	s_cmpk_lt_u32 s9, 0x440
	s_cbranch_scc1 .Ltrm_p3_c0
	s_cmpk_lt_u32 s9, 0xc40
	s_cbranch_scc1 .Ltrm_p3_c1
	s_cmpk_lt_u32 s9, 0x1440
	s_cbranch_scc1 .Ltrm_p3_c2
	s_cmpk_lt_u32 s9, 0x1540
	s_cbranch_scc1 .Ltrm_p3_c3
	s_sub_u32 s7, s9, 0x1540
	s_mov_b64 s[70:71], s[80:81]
	s_mov_b64 s[28:29], s[82:83]
	s_mov_b64 s[34:35], s[86:87]
	s_mov_b32 s8, 10
	s_mov_b32 s22, 10
	s_mov_b32 s91, 1
	s_branch .Ltrm_p3_cm

.Ltrm_l4_x:
	global_load_dword v16, v[62:63], off nt
	v_lshl_add_u64 v[62:63], v[62:63], 0, s[30:31]
	global_load_dword v17, v[62:63], off nt
	v_lshl_add_u64 v[62:63], v[62:63], 0, s[30:31]
	global_load_dword v18, v[62:63], off nt
	v_lshl_add_u64 v[62:63], v[62:63], 0, s[30:31]
	global_load_dword v19, v[62:63], off nt
	v_lshl_add_u64 v[62:63], v[62:63], 0, s[30:31]
	global_load_dword v20, v[62:63], off nt
	v_lshl_add_u64 v[62:63], v[62:63], 0, s[30:31]
	global_load_dword v21, v[62:63], off nt
	v_lshl_add_u64 v[62:63], v[62:63], 0, s[30:31]
	global_load_dword v22, v[62:63], off nt
	v_lshl_add_u64 v[62:63], v[62:63], 0, s[30:31]
	global_load_dword v23, v[62:63], off nt
	v_lshl_add_u64 v[62:63], v[62:63], 0, s[30:31]
	global_load_dword v24, v[62:63], off nt
	v_lshl_add_u64 v[62:63], v[62:63], 0, s[30:31]
	global_load_dword v25, v[62:63], off nt
	v_lshl_add_u64 v[62:63], v[62:63], 0, s[30:31]
	global_load_dword v26, v[62:63], off nt
	v_lshl_add_u64 v[62:63], v[62:63], 0, s[30:31]
	global_load_dword v27, v[62:63], off nt
	v_lshl_add_u64 v[62:63], v[62:63], 0, s[30:31]
	global_load_dword v28, v[62:63], off nt
	v_lshl_add_u64 v[62:63], v[62:63], 0, s[30:31]
	global_load_dword v29, v[62:63], off nt
	v_lshl_add_u64 v[62:63], v[62:63], 0, s[30:31]
	global_load_dword v30, v[62:63], off nt
	v_lshl_add_u64 v[62:63], v[62:63], 0, s[30:31]
	global_load_dword v31, v[62:63], off nt
	s_waitcnt vmcnt(16)
	s_barrier
	ds_write_b32 v38, v0 offset:0
	ds_write_b32 v38, v1 offset:1040
	ds_write_b32 v38, v2 offset:2080
	ds_write_b32 v38, v3 offset:3120
	ds_write_b32 v38, v4 offset:4160
	ds_write_b32 v38, v5 offset:5200
	ds_write_b32 v38, v6 offset:6240
	ds_write_b32 v38, v7 offset:7280
	ds_write_b32 v38, v8 offset:8320
	ds_write_b32 v38, v9 offset:9360
	ds_write_b32 v38, v10 offset:10400
	ds_write_b32 v38, v11 offset:11440
	ds_write_b32 v38, v12 offset:12480
	ds_write_b32 v38, v13 offset:13520
	ds_write_b32 v38, v14 offset:14560
	ds_write_b32 v38, v15 offset:15600
	v_lshl_add_u32 v46, v41, s20, v42
	s_waitcnt lgkmcnt(0)
	s_barrier
	ds_read2_b32 v[66:67], v40 offset0:0 offset1:32
	ds_read2_b32 v[68:69], v40 offset0:65 offset1:97
	ds_read2_b32 v[70:71], v40 offset0:130 offset1:162
	ds_read2_b32 v[72:73], v40 offset0:195 offset1:227
	ds_read2_b32 v[74:75], v44 offset0:4 offset1:36
	ds_read2_b32 v[76:77], v44 offset0:69 offset1:101
	ds_read2_b32 v[78:79], v44 offset0:134 offset1:166
	ds_read2_b32 v[80:81], v44 offset0:199 offset1:231
	v_lshl_add_u64 v[48:49], s[16:17], 0, v[46:47]
	v_lshl_add_u64 v[50:51], v[48:49], 0, s[18:19]
	s_waitcnt lgkmcnt(6)
	v_cvt_pk_bf16_f32 v52, v66, v68
	v_cvt_pk_bf16_f32 v56, v67, v69
	s_waitcnt lgkmcnt(4)
	v_cvt_pk_bf16_f32 v53, v70, v72
	v_cvt_pk_bf16_f32 v57, v71, v73
	s_waitcnt lgkmcnt(2)
	v_cvt_pk_bf16_f32 v54, v74, v76
	v_cvt_pk_bf16_f32 v58, v75, v77
	s_waitcnt lgkmcnt(0)
	v_cvt_pk_bf16_f32 v55, v78, v80
	v_cvt_pk_bf16_f32 v59, v79, v81
	global_store_dwordx4 v[48:49], v[52:55], off
	global_store_dwordx4 v[50:51], v[56:59], off
	s_addk_i32 s9, 0x100
	s_cmpk_lt_u32 s9, 0x740
	s_cbranch_scc0 .Ltrm_last2
	s_cmpk_lt_u32 s9, 0x440
	s_cbranch_scc1 .Ltrm_p5_c0
	s_cmpk_lt_u32 s9, 0xc40
	s_cbranch_scc1 .Ltrm_p5_c1
	s_cmpk_lt_u32 s9, 0x1440
	s_cbranch_scc1 .Ltrm_p5_c2
	s_cmpk_lt_u32 s9, 0x1540
	s_cbranch_scc1 .Ltrm_p5_c3
	s_sub_u32 s7, s9, 0x1540
	s_mov_b64 s[70:71], s[80:81]
	s_mov_b64 s[12:13], s[82:83]
	s_mov_b64 s[16:17], s[86:87]
	s_mov_b32 s8, 10
	s_mov_b32 s22, 10
	s_mov_b32 s21, 1
	s_branch .Ltrm_p5_cm

.Ltrm_skip:
	s_cmp_lt_u32 s2, 128
	s_cbranch_scc1 .Ltrq_skip
	s_load_dword s4, s[0:1], 0x148
	s_waitcnt lgkmcnt(0)
	s_cmpk_lg_i32 s4, 0x100
	s_cbranch_scc1 .Ltrq_skip
	s_sub_u32 s3, s2, 128
	s_lshl_b32 s3, s3, 1
	s_addk_i32 s3, 0x740
	s_cmpk_gt_i32 s3, 0x173f
	s_cbranch_scc1 .Ltrq_done
	s_load_dwordx4 s[72:75], s[0:1], 0x48
	s_load_dwordx2 s[76:77], s[0:1], 0x78
	s_load_dwordx2 s[78:79], s[0:1], 0x80
	s_load_dwordx4 s[80:83], s[0:1], 0xc8
	s_load_dwordx4 s[84:87], s[0:1], 0x100
	v_and_b32_e32 v32, 63, v129
	v_lshlrev_b32_e32 v82, 2, v32
	v_mov_b32_e32 v83, 0
	v_lshrrev_b32_e32 v84, 5, v32
	v_lshlrev_b32_e32 v84, 4, v84
	v_and_b32_e32 v85, 15, v32
	v_add_u32_e32 v84, v84, v85
	v_lshlrev_b32_e32 v84, 2, v84
	v_mov_b32_e32 v85, 0
	v_and_b32_e32 v37, 16, v32
	v_cmp_ne_u32_e64 s[68:69], 0, v37
	v_readfirstlane_b32 s4, v129
	s_lshr_b32 s4, s4, 6
	s_lshr_b32 s5, s4, 2
	s_and_b32 s6, s4, 3
	s_lshl_b32 s7, s5, 15
	s_mul_i32 s8, s6, 0x104
	s_add_u32 s8, s7, s8
	v_add_u32_e32 v38, s8, v82
	v_and_b32_e32 v39, 7, v129
	v_lshlrev_b32_e32 v39, 3, v39
	v_mul_u32_u24_e32 v40, 0x104, v39
	v_bfe_u32 v41, v129, 3, 5
	v_lshl_add_u32 v40, v41, 2, v40
	v_add_u32_e32 v40, s7, v40
	v_add_u32_e32 v44, 0x400, v40
	v_lshlrev_b32_e32 v42, 1, v39
	v_mov_b32_e32 v47, 0
	s_add_u32 s9, s3, s5
	s_waitcnt lgkmcnt(0)
	s_cmpk_lt_u32 s9, 0x440
	s_cbranch_scc1 .Ltrq_p1_c0
	s_cmpk_lt_u32 s9, 0xc40
	s_cbranch_scc1 .Ltrq_p1_c1
	s_cmpk_lt_u32 s9, 0x1440
	s_cbranch_scc1 .Ltrq_p1_c2
	s_cmpk_lt_u32 s9, 0x1540
	s_cbranch_scc1 .Ltrq_p1_c3
	s_sub_u32 s7, s9, 0x1540
	s_mov_b64 s[70:71], s[80:81]
	s_mov_b64 s[12:13], s[82:83]
	s_mov_b64 s[16:17], s[86:87]
	s_mov_b32 s8, 10
	s_mov_b32 s22, 10
	s_mov_b32 s21, 1
	s_branch .Ltrq_p1_cm
